# v47 + mode-1 attention: drop 8 v_mov_b64 negm copies per 2-step iteration (step 2 reads -m from its own registers)
# speedup vs baseline: 1.0167x; 1.0167x over previous
.LBB0_399:
	s_setprio 3
	s_add_i32 s34, s56, 0xfffc0000
	s_add_i32 s30, s55, -1
	s_and_b32 s34, s34, 0xf00000
	s_and_b32 s30, s30, 3
	s_lshl_b32 s78, s34, 1
	s_add_i32 s54, s29, 0
	s_mul_i32 s58, s30, 0x38000
	s_mov_b32 s59, s79
	s_add_u32 s98, s78, s58
	s_addc_u32 s99, s79, s79
	s_add_i32 s34, s54, s5
	v_lshl_add_u64 v[34:35], v[116:117], 0, s[98:99]
	s_mov_b32 m0, s34
	s_add_i32 s35, s34, 0x2000
	global_load_lds_dwordx4 v[34:35], off
	v_lshl_add_u64 v[34:35], v[118:119], 0, s[98:99]
	s_mov_b32 m0, s35
	s_mov_b32 s30, s27
	global_load_lds_dwordx4 v[34:35], off
	s_mov_b32 s27, s72
	s_add_i32 s53, s30, 0
	v_add_u32_e32 v0, s53, v126
	ds_read_b128 v[34:37], v0
	ds_read_b128 v[38:41], v0 offset:2048
	v_exp_f32_e32 v145, v66
	v_exp_f32_e32 v146, v67
	v_exp_f32_e32 v147, v68
	v_exp_f32_e32 v148, v69
	v_exp_f32_e32 v149, v70
	v_exp_f32_e32 v150, v71
	v_exp_f32_e32 v151, v72
	s_waitcnt lgkmcnt(0)
	v_mfma_f32_32x32x16_bf16 v[82:97], v[34:37], v[110:113], v[50:65]
	ds_read_b128 v[34:37], v0 offset:4096
	v_exp_f32_e32 v152, v73
	v_exp_f32_e32 v153, v74
	v_exp_f32_e32 v154, v75
	v_exp_f32_e32 v155, v76
	v_exp_f32_e32 v156, v77
	v_exp_f32_e32 v157, v78
	v_mfma_f32_32x32x16_bf16 v[82:97], v[38:41], v[106:109], v[82:97]
	ds_read_b128 v[38:41], v0 offset:6144
	v_exp_f32_e32 v158, v79
	v_exp_f32_e32 v159, v80
	v_exp_f32_e32 v160, v81
	s_waitcnt lgkmcnt(0)
	v_mfma_f32_32x32x16_bf16 v[82:97], v[34:37], v[102:105], v[82:97]
	v_add_f32_e32 v34, v129, v131
	v_add_f32_e32 v66, v132, v34
	ds_read_b128 v[34:37], v0 offset:512
	ds_read_b128 v[42:45], v0 offset:2560
	ds_read_b128 v[46:49], v0 offset:4608
	v_mfma_f32_32x32x16_bf16 v[82:97], v[38:41], v[98:101], v[82:97]
	ds_read_b128 v[38:41], v0 offset:6656
	v_add_f32_e32 v0, v135, v66
	v_add_f32_e32 v0, v136, v0
	v_add_f32_e32 v0, v139, v0
	v_add_f32_e32 v0, v140, v0
	v_add_f32_e32 v0, v143, v0
	v_add_f32_e32 v0, v130, v0
	s_waitcnt lgkmcnt(0)
	v_mfma_f32_32x32x16_bf16 v[66:81], v[34:37], v[110:113], v[50:65]
	v_add_f32_e32 v0, v133, v0
	v_add_f32_e32 v0, v134, v0
	v_add_f32_e32 v0, v137, v0
	v_add_f32_e32 v0, v138, v0
	s_setprio 2
	v_add_f32_e32 v0, v141, v0
	v_add_f32_e32 v0, v142, v0
	v_add_f32_e32 v0, v144, v0
	v_mfma_f32_32x32x16_bf16 v[66:81], v[42:45], v[106:109], v[66:81]
	v_add_f32_e32 v0, v145, v0
	v_add_f32_e32 v0, v146, v0
	v_add_f32_e32 v0, v147, v0
	v_add_f32_e32 v0, v148, v0
	v_add_f32_e32 v0, v149, v0
	v_add_f32_e32 v0, v150, v0
	v_add_f32_e32 v0, v151, v0
	v_mfma_f32_32x32x16_bf16 v[66:81], v[46:49], v[102:105], v[66:81]
	v_add_f32_e32 v0, v152, v0
	v_add_f32_e32 v0, v153, v0
	v_add_f32_e32 v0, v154, v0
	v_add_f32_e32 v0, v155, v0
	v_add_f32_e32 v0, v156, v0
	v_add_f32_e32 v0, v157, v0
	v_add_f32_e32 v0, v158, v0
	v_mfma_f32_32x32x16_bf16 v[66:81], v[38:41], v[98:101], v[66:81]
	v_cvt_pk_bf16_f32 v34, v129, v131
	v_add_f32_e32 v161, v159, v0
	v_cvt_pk_bf16_f32 v35, v132, v135
	v_cvt_pk_bf16_f32 v36, v136, v139
	v_cvt_pk_bf16_f32 v37, v140, v143
	v_cvt_pk_bf16_f32 v38, v130, v133
	v_cvt_pk_bf16_f32 v39, v134, v137
	v_cvt_pk_bf16_f32 v40, v138, v141
	v_cvt_pk_bf16_f32 v41, v142, v144
	v_cvt_pk_bf16_f32 v42, v145, v146
	v_cvt_pk_bf16_f32 v43, v147, v148
	v_cvt_pk_bf16_f32 v44, v149, v150
	v_cvt_pk_bf16_f32 v45, v151, v152
	v_cvt_pk_bf16_f32 v46, v153, v154
	v_cvt_pk_bf16_f32 v47, v155, v156
	v_cvt_pk_bf16_f32 v48, v157, v158
	v_cvt_pk_bf16_f32 v49, v159, v160
	s_add_i32 s57, s72, 0
	v_add_u32_e32 v0, s57, v125
	ds_read_b64_tr_b16 v[130:131], v0 offset:8192
	ds_read_b64_tr_b16 v[132:133], v0 offset:8704
	ds_read_b64_tr_b16 v[134:135], v0 offset:12288
	v_max_f32_e32 v129, v67, v67
	s_waitcnt lgkmcnt(1)
	v_mfma_f32_32x32x16_bf16 v[18:33], v[130:133], v[34:37], v[18:33]
	ds_read_b64_tr_b16 v[136:137], v0 offset:12800
	ds_read_b64_tr_b16 v[130:131], v0 offset:9216
	s_waitcnt lgkmcnt(1)
	v_mfma_f32_32x32x16_bf16 v[2:17], v[134:137], v[34:37], v[2:17]
	ds_read_b64_tr_b16 v[132:133], v0 offset:9728
	ds_read_b64_tr_b16 v[34:35], v0 offset:13312
	s_waitcnt lgkmcnt(1)
	v_mfma_f32_32x32x16_bf16 v[18:33], v[130:133], v[38:41], v[18:33]
	ds_read_b64_tr_b16 v[36:37], v0 offset:13824
	ds_read_b64_tr_b16 v[130:131], v0 offset:10240
	s_waitcnt lgkmcnt(1)
	v_mfma_f32_32x32x16_bf16 v[2:17], v[34:37], v[38:41], v[2:17]
	ds_read_b64_tr_b16 v[132:133], v0 offset:10752
	ds_read_b64_tr_b16 v[34:35], v0 offset:11264
	ds_read_b64_tr_b16 v[36:37], v0 offset:11776
	ds_read_b64_tr_b16 v[38:39], v0 offset:14336
	ds_read_b64_tr_b16 v[40:41], v0 offset:14848
	ds_read_b64_tr_b16 v[134:135], v0 offset:15360
	ds_read_b64_tr_b16 v[136:137], v0 offset:15872
	s_waitcnt lgkmcnt(6)
	v_mfma_f32_32x32x16_bf16 v[18:33], v[130:133], v[42:45], v[18:33]
	v_max_f32_e32 v130, v83, v83
	v_max_f32_e32 v129, v130, v129
	v_max3_f32 v130, v82, v66, v84
	s_setprio 1
	v_max3_f32 v129, v129, v85, v69
	v_max3_f32 v130, v130, v68, v86
	v_max3_f32 v129, v129, v87, v71
	s_waitcnt lgkmcnt(2)
	v_mfma_f32_32x32x16_bf16 v[2:17], v[38:41], v[42:45], v[2:17]
	v_max3_f32 v38, v130, v70, v88
	v_max3_f32 v39, v129, v89, v73
	v_max3_f32 v38, v38, v72, v90
	v_max3_f32 v39, v39, v91, v75
	v_max3_f32 v38, v38, v74, v92
	v_max3_f32 v39, v39, v93, v77
	v_max3_f32 v38, v38, v76, v94
	v_mfma_f32_32x32x16_bf16 v[18:33], v[34:37], v[46:49], v[18:33]
	v_max3_f32 v34, v39, v95, v79
	v_max3_f32 v35, v38, v78, v96
	v_max3_f32 v34, v34, v97, v81
	v_add_f32_e32 v36, v160, v161
	v_max3_f32 v34, v35, v80, v34
	v_add_f32_e32 v128, v128, v36
	v_cmp_lt_f32_e32 vcc, s33, v34
	s_waitcnt lgkmcnt(0)
	v_mfma_f32_32x32x16_bf16 v[2:17], v[134:137], v[46:49], v[2:17]
	s_cbranch_vccz .LBB0_401
	v_mov_b32_e32 v35, v34
	s_nop 1
	v_permlane32_swap_b32 v34, v35
	s_nop 1
	s_nop 0
	v_max3_f32 v36, v34, v35, 0
	v_exp_f32_e64 v38, -v36
	v_add_f32_e32 v127, v127, v36
	v_xor_b32_e32 v34, 0x80000000, v127
	v_pk_add_f32 v[82:83], v[82:83], v[36:37] op_sel_hi:[1,0] neg_lo:[0,1] neg_hi:[0,1]
	v_pk_add_f32 v[66:67], v[66:67], v[36:37] op_sel_hi:[1,0] neg_lo:[0,1] neg_hi:[0,1]
	v_pk_add_f32 v[84:85], v[84:85], v[36:37] op_sel_hi:[1,0] neg_lo:[0,1] neg_hi:[0,1]
	v_pk_add_f32 v[68:69], v[68:69], v[36:37] op_sel_hi:[1,0] neg_lo:[0,1] neg_hi:[0,1]
	v_pk_add_f32 v[86:87], v[86:87], v[36:37] op_sel_hi:[1,0] neg_lo:[0,1] neg_hi:[0,1]
	v_pk_add_f32 v[70:71], v[70:71], v[36:37] op_sel_hi:[1,0] neg_lo:[0,1] neg_hi:[0,1]
	v_pk_add_f32 v[88:89], v[88:89], v[36:37] op_sel_hi:[1,0] neg_lo:[0,1] neg_hi:[0,1]
	v_pk_add_f32 v[72:73], v[72:73], v[36:37] op_sel_hi:[1,0] neg_lo:[0,1] neg_hi:[0,1]
	v_pk_add_f32 v[90:91], v[90:91], v[36:37] op_sel_hi:[1,0] neg_lo:[0,1] neg_hi:[0,1]
	v_pk_add_f32 v[74:75], v[74:75], v[36:37] op_sel_hi:[1,0] neg_lo:[0,1] neg_hi:[0,1]
	v_pk_add_f32 v[92:93], v[92:93], v[36:37] op_sel_hi:[1,0] neg_lo:[0,1] neg_hi:[0,1]
	v_pk_add_f32 v[76:77], v[76:77], v[36:37] op_sel_hi:[1,0] neg_lo:[0,1] neg_hi:[0,1]
	v_pk_add_f32 v[94:95], v[94:95], v[36:37] op_sel_hi:[1,0] neg_lo:[0,1] neg_hi:[0,1]
	v_pk_add_f32 v[78:79], v[78:79], v[36:37] op_sel_hi:[1,0] neg_lo:[0,1] neg_hi:[0,1]
	v_pk_add_f32 v[96:97], v[96:97], v[36:37] op_sel_hi:[1,0] neg_lo:[0,1] neg_hi:[0,1]
	v_pk_add_f32 v[80:81], v[80:81], v[36:37] op_sel_hi:[1,0] neg_lo:[0,1] neg_hi:[0,1]
	v_pk_mul_f32 v[32:33], v[32:33], v[38:39] op_sel_hi:[1,0]
	v_pk_mul_f32 v[30:31], v[30:31], v[38:39] op_sel_hi:[1,0]
	v_pk_mul_f32 v[28:29], v[28:29], v[38:39] op_sel_hi:[1,0]
	v_pk_mul_f32 v[26:27], v[26:27], v[38:39] op_sel_hi:[1,0]
	v_pk_mul_f32 v[24:25], v[24:25], v[38:39] op_sel_hi:[1,0]
	v_pk_mul_f32 v[22:23], v[22:23], v[38:39] op_sel_hi:[1,0]
	v_pk_mul_f32 v[20:21], v[20:21], v[38:39] op_sel_hi:[1,0]
	v_pk_mul_f32 v[18:19], v[18:19], v[38:39] op_sel_hi:[1,0]
	v_pk_mul_f32 v[16:17], v[16:17], v[38:39] op_sel_hi:[1,0]
	v_pk_mul_f32 v[14:15], v[14:15], v[38:39] op_sel_hi:[1,0]
	v_pk_mul_f32 v[12:13], v[12:13], v[38:39] op_sel_hi:[1,0]
	v_pk_mul_f32 v[10:11], v[10:11], v[38:39] op_sel_hi:[1,0]
	v_pk_mul_f32 v[8:9], v[8:9], v[38:39] op_sel_hi:[1,0]
	v_pk_mul_f32 v[6:7], v[6:7], v[38:39] op_sel_hi:[1,0]
	v_pk_mul_f32 v[4:5], v[4:5], v[38:39] op_sel_hi:[1,0]
	v_pk_mul_f32 v[2:3], v[2:3], v[38:39] op_sel_hi:[1,0]
	v_mul_f32_e32 v128, v128, v38
	v_mov_b32_e32 v35, v34
	v_mov_b32_e32 v36, v34
	v_mov_b32_e32 v37, v34
	v_mov_b32_e32 v38, v34
	v_mov_b32_e32 v39, v34
	v_mov_b32_e32 v40, v34
	v_mov_b32_e32 v41, v34
	v_mov_b32_e32 v42, v34
	v_mov_b32_e32 v43, v34
	v_mov_b32_e32 v44, v34
	v_mov_b32_e32 v45, v34
	v_mov_b32_e32 v46, v34
	v_mov_b32_e32 v47, v34
	v_mov_b32_e32 v48, v34
	v_mov_b32_e32 v49, v34
	v_mov_b32_e32 v50, v34
	v_mov_b32_e32 v51, v34
	v_mov_b32_e32 v52, v34
	v_mov_b32_e32 v53, v34
	v_mov_b32_e32 v54, v34
	v_mov_b32_e32 v55, v34
	v_mov_b32_e32 v56, v34
	v_mov_b32_e32 v57, v34
	v_mov_b32_e32 v58, v34
	v_mov_b32_e32 v59, v34
	v_mov_b32_e32 v60, v34
	v_mov_b32_e32 v61, v34
	v_mov_b32_e32 v62, v34
	v_mov_b32_e32 v63, v34
	v_mov_b32_e32 v64, v34
	v_mov_b32_e32 v65, v34
	s_branch .LBB0_402
.LBB0_401:
.LBB0_402:
	v_exp_f32_e32 v129, v82
	s_setprio 0
	v_exp_f32_e32 v146, v83
	v_exp_f32_e32 v147, v84
	v_exp_f32_e32 v148, v85
	v_exp_f32_e32 v149, v86
	v_exp_f32_e32 v150, v87
	v_exp_f32_e32 v151, v88
	v_exp_f32_e32 v152, v89
	v_exp_f32_e32 v153, v90
	v_exp_f32_e32 v154, v91
	v_exp_f32_e32 v155, v92
	v_exp_f32_e32 v156, v93
	v_exp_f32_e32 v157, v94
	v_exp_f32_e32 v158, v95
	v_exp_f32_e32 v159, v96
	v_exp_f32_e32 v160, v97
	s_add_i32 s58, s55, 4
	s_and_b32 s59, s56, 0xf00000
	s_and_b32 s58, s58, 3
	s_lshl_b32 s78, s59, 1
	s_mul_i32 s58, s58, 0x38000
	s_mov_b32 s59, s79
	s_add_u32 s98, s78, s58
	s_addc_u32 s99, s79, s79
	s_add_i32 s60, s57, s5
	v_lshl_add_u64 v[82:83], v[116:117], 0, s[98:99]
	s_mov_b32 m0, s60
	s_waitcnt vmcnt(0)
	s_barrier
	s_setprio 3
	global_load_lds_dwordx4 v[82:83], off
	v_lshl_add_u64 v[82:83], v[118:119], 0, s[98:99]
	s_add_i32 m0, s60, 0x2000
	s_nop 0
	global_load_lds_dwordx4 v[82:83], off
	v_add_u32_e32 v142, s54, v126
	ds_read_b128 v[130:133], v142
	ds_read_b128 v[134:137], v142 offset:2048
	v_exp_f32_e32 v161, v66
	v_exp_f32_e32 v162, v67
	v_exp_f32_e32 v163, v68
	v_exp_f32_e32 v164, v69
	ds_read_b128 v[66:69], v142 offset:4096
	v_exp_f32_e32 v165, v70
	v_exp_f32_e32 v166, v71
	s_waitcnt lgkmcnt(0)
	v_mfma_f32_32x32x16_bf16 v[82:97], v[130:133], v[110:113], v[50:65]
	v_exp_f32_e32 v167, v72
	v_exp_f32_e32 v168, v73
	ds_read_b128 v[70:73], v142 offset:6144
	v_exp_f32_e32 v169, v74
	v_exp_f32_e32 v170, v75
	v_exp_f32_e32 v171, v76
	v_exp_f32_e32 v172, v77
	v_mfma_f32_32x32x16_bf16 v[82:97], v[134:137], v[106:109], v[82:97]
	ds_read_b128 v[130:133], v142 offset:512
	ds_read_b128 v[134:137], v142 offset:2560
	ds_read_b128 v[138:141], v142 offset:4608
	ds_read_b128 v[142:145], v142 offset:6656
	v_exp_f32_e32 v173, v78
	v_exp_f32_e32 v174, v79
	v_exp_f32_e32 v175, v80
	v_exp_f32_e32 v176, v81
	v_mfma_f32_32x32x16_bf16 v[82:97], v[66:69], v[102:105], v[82:97]
	v_add_f32_e32 v66, v129, v146
	v_add_f32_e32 v66, v147, v66
	v_add_f32_e32 v66, v148, v66
	v_add_f32_e32 v66, v149, v66
	v_add_f32_e32 v66, v150, v66
	v_add_f32_e32 v66, v151, v66
	v_add_f32_e32 v66, v152, v66
	v_add_f32_e32 v66, v153, v66
	s_waitcnt lgkmcnt(0)
	v_mfma_f32_32x32x16_bf16 v[82:97], v[70:73], v[98:101], v[82:97]
	v_add_f32_e32 v177, v154, v66
	v_mfma_f32_32x32x16_bf16 v[66:81], v[130:133], v[110:113], v[50:65]
	v_add_f32_e32 v130, v155, v177
	v_add_f32_e32 v130, v156, v130
	v_add_f32_e32 v130, v157, v130
	v_add_f32_e32 v130, v158, v130
	v_add_f32_e32 v130, v159, v130
	v_add_f32_e32 v130, v160, v130
	v_add_f32_e32 v130, v161, v130
	v_mfma_f32_32x32x16_bf16 v[66:81], v[134:137], v[106:109], v[66:81]
	v_add_f32_e32 v130, v162, v130
	v_add_f32_e32 v130, v163, v130
	v_add_f32_e32 v130, v164, v130
	v_add_f32_e32 v130, v165, v130
	v_add_f32_e32 v130, v166, v130
	v_add_f32_e32 v130, v167, v130
	s_setprio 2
	v_add_f32_e32 v130, v168, v130
	v_mfma_f32_32x32x16_bf16 v[66:81], v[138:141], v[102:105], v[66:81]
	v_add_f32_e32 v130, v169, v130
	v_add_f32_e32 v130, v170, v130
	v_add_f32_e32 v130, v171, v130
	v_add_f32_e32 v130, v172, v130
	v_add_f32_e32 v130, v173, v130
	v_add_f32_e32 v130, v174, v130
	v_add_f32_e32 v177, v175, v130
	v_mfma_f32_32x32x16_bf16 v[66:81], v[142:145], v[98:101], v[66:81]
	v_cvt_pk_bf16_f32 v130, v129, v146
	v_cvt_pk_bf16_f32 v131, v147, v148
	v_cvt_pk_bf16_f32 v132, v149, v150
	v_cvt_pk_bf16_f32 v133, v151, v152
	v_cvt_pk_bf16_f32 v134, v153, v154
	v_cvt_pk_bf16_f32 v135, v155, v156
	v_cvt_pk_bf16_f32 v136, v157, v158
	v_cvt_pk_bf16_f32 v137, v159, v160
	v_cvt_pk_bf16_f32 v138, v161, v162
	v_cvt_pk_bf16_f32 v139, v163, v164
	v_cvt_pk_bf16_f32 v140, v165, v166
	v_cvt_pk_bf16_f32 v141, v167, v168
	v_cvt_pk_bf16_f32 v142, v169, v170
	v_cvt_pk_bf16_f32 v143, v171, v172
	v_cvt_pk_bf16_f32 v144, v173, v174
	v_cvt_pk_bf16_f32 v145, v175, v176
	v_add_u32_e32 v129, s53, v125
	ds_read_b64_tr_b16 v[146:147], v129 offset:8192
	ds_read_b64_tr_b16 v[148:149], v129 offset:8704
	ds_read_b64_tr_b16 v[150:151], v129 offset:12288
	s_waitcnt lgkmcnt(1)
	v_mfma_f32_32x32x16_bf16 v[18:33], v[146:149], v[130:133], v[18:33]
	ds_read_b64_tr_b16 v[152:153], v129 offset:12800
	ds_read_b64_tr_b16 v[146:147], v129 offset:9216
	s_waitcnt lgkmcnt(1)
	v_mfma_f32_32x32x16_bf16 v[2:17], v[150:153], v[130:133], v[2:17]
	ds_read_b64_tr_b16 v[148:149], v129 offset:9728
	ds_read_b64_tr_b16 v[130:131], v129 offset:13312
	s_waitcnt lgkmcnt(1)
	v_mfma_f32_32x32x16_bf16 v[18:33], v[146:149], v[134:137], v[18:33]
	ds_read_b64_tr_b16 v[132:133], v129 offset:13824
	ds_read_b64_tr_b16 v[146:147], v129 offset:10240
	s_waitcnt lgkmcnt(1)
	v_mfma_f32_32x32x16_bf16 v[2:17], v[130:133], v[134:137], v[2:17]
	ds_read_b64_tr_b16 v[148:149], v129 offset:10752
	ds_read_b64_tr_b16 v[130:131], v129 offset:11264
	ds_read_b64_tr_b16 v[132:133], v129 offset:11776
	ds_read_b64_tr_b16 v[134:135], v129 offset:14336
	ds_read_b64_tr_b16 v[136:137], v129 offset:14848
	ds_read_b64_tr_b16 v[150:151], v129 offset:15360
	ds_read_b64_tr_b16 v[152:153], v129 offset:15872
	v_max_f32_e32 v129, v67, v67
	s_waitcnt lgkmcnt(6)
	v_mfma_f32_32x32x16_bf16 v[18:33], v[146:149], v[138:141], v[18:33]
	v_max_f32_e32 v146, v83, v83
	v_max_f32_e32 v129, v146, v129
	v_max3_f32 v146, v82, v66, v84
	v_max3_f32 v129, v129, v85, v69
	v_max3_f32 v146, v146, v68, v86
	v_max3_f32 v129, v129, v87, v71
	v_max3_f32 v129, v129, v89, v73
	s_waitcnt lgkmcnt(2)
	s_setprio 1
	v_mfma_f32_32x32x16_bf16 v[2:17], v[134:137], v[138:141], v[2:17]
	v_max3_f32 v134, v146, v70, v88
	v_max3_f32 v134, v134, v72, v90
	v_max3_f32 v129, v129, v91, v75
	v_max3_f32 v134, v134, v74, v92
	v_max3_f32 v129, v129, v93, v77
	v_max3_f32 v134, v134, v76, v94
	v_max3_f32 v129, v129, v95, v79
	v_mfma_f32_32x32x16_bf16 v[18:33], v[130:133], v[142:145], v[18:33]
	v_max3_f32 v130, v134, v78, v96
	v_max3_f32 v129, v129, v97, v81
	v_add_f32_e32 v131, v176, v177
	v_max3_f32 v129, v130, v80, v129
	v_add_f32_e32 v128, v128, v131
	v_cmp_lt_f32_e32 vcc, s33, v129
	s_waitcnt lgkmcnt(0)
	v_mfma_f32_32x32x16_bf16 v[2:17], v[150:153], v[142:145], v[2:17]
	s_cbranch_vccz .LBB0_404
	v_mov_b32_e32 v34, v129
	s_nop 1
	v_permlane32_swap_b32 v129, v34
	s_nop 1
	s_nop 0
	v_max3_f32 v36, v129, v34, 0
	v_exp_f32_e64 v38, -v36
	v_add_f32_e32 v127, v127, v36
	v_xor_b32_e32 v34, 0x80000000, v127
	v_pk_add_f32 v[82:83], v[82:83], v[36:37] op_sel_hi:[1,0] neg_lo:[0,1] neg_hi:[0,1]
	v_pk_add_f32 v[84:85], v[84:85], v[36:37] op_sel_hi:[1,0] neg_lo:[0,1] neg_hi:[0,1]
	v_pk_add_f32 v[86:87], v[86:87], v[36:37] op_sel_hi:[1,0] neg_lo:[0,1] neg_hi:[0,1]
	v_pk_add_f32 v[88:89], v[88:89], v[36:37] op_sel_hi:[1,0] neg_lo:[0,1] neg_hi:[0,1]
	v_pk_add_f32 v[90:91], v[90:91], v[36:37] op_sel_hi:[1,0] neg_lo:[0,1] neg_hi:[0,1]
	v_pk_add_f32 v[92:93], v[92:93], v[36:37] op_sel_hi:[1,0] neg_lo:[0,1] neg_hi:[0,1]
	v_pk_add_f32 v[94:95], v[94:95], v[36:37] op_sel_hi:[1,0] neg_lo:[0,1] neg_hi:[0,1]
	v_pk_add_f32 v[96:97], v[96:97], v[36:37] op_sel_hi:[1,0] neg_lo:[0,1] neg_hi:[0,1]
	v_sub_f32_e32 v81, v81, v36
	v_sub_f32_e32 v80, v80, v36
	v_sub_f32_e32 v79, v79, v36
	v_sub_f32_e32 v78, v78, v36
	v_sub_f32_e32 v77, v77, v36
	v_sub_f32_e32 v76, v76, v36
	v_sub_f32_e32 v75, v75, v36
	v_sub_f32_e32 v74, v74, v36
	v_sub_f32_e32 v73, v73, v36
	v_sub_f32_e32 v72, v72, v36
	v_sub_f32_e32 v71, v71, v36
	v_sub_f32_e32 v70, v70, v36
	v_sub_f32_e32 v69, v69, v36
	v_sub_f32_e32 v68, v68, v36
	v_sub_f32_e32 v67, v67, v36
	v_sub_f32_e32 v66, v66, v36
	v_pk_mul_f32 v[32:33], v[32:33], v[38:39] op_sel_hi:[1,0]
	v_pk_mul_f32 v[30:31], v[30:31], v[38:39] op_sel_hi:[1,0]
	v_pk_mul_f32 v[28:29], v[28:29], v[38:39] op_sel_hi:[1,0]
	v_pk_mul_f32 v[26:27], v[26:27], v[38:39] op_sel_hi:[1,0]
	v_pk_mul_f32 v[24:25], v[24:25], v[38:39] op_sel_hi:[1,0]
	v_pk_mul_f32 v[22:23], v[22:23], v[38:39] op_sel_hi:[1,0]
	v_pk_mul_f32 v[20:21], v[20:21], v[38:39] op_sel_hi:[1,0]
	v_pk_mul_f32 v[18:19], v[18:19], v[38:39] op_sel_hi:[1,0]
	v_pk_mul_f32 v[16:17], v[16:17], v[38:39] op_sel_hi:[1,0]
	v_pk_mul_f32 v[14:15], v[14:15], v[38:39] op_sel_hi:[1,0]
	v_pk_mul_f32 v[12:13], v[12:13], v[38:39] op_sel_hi:[1,0]
	v_pk_mul_f32 v[10:11], v[10:11], v[38:39] op_sel_hi:[1,0]
	v_pk_mul_f32 v[8:9], v[8:9], v[38:39] op_sel_hi:[1,0]
	v_pk_mul_f32 v[6:7], v[6:7], v[38:39] op_sel_hi:[1,0]
	v_pk_mul_f32 v[4:5], v[4:5], v[38:39] op_sel_hi:[1,0]
	v_pk_mul_f32 v[2:3], v[2:3], v[38:39] op_sel_hi:[1,0]
	v_mul_f32_e32 v128, v128, v38
	v_mov_b32_e32 v35, v34
	v_mov_b32_e32 v36, v34
	v_mov_b32_e32 v37, v34
	v_mov_b32_e32 v38, v34
	v_mov_b32_e32 v39, v34
	v_mov_b32_e32 v40, v34
	v_mov_b32_e32 v41, v34
	v_mov_b32_e32 v42, v34
	v_mov_b32_e32 v43, v34
	v_mov_b32_e32 v44, v34
	v_mov_b32_e32 v45, v34
	v_mov_b32_e32 v46, v34
	v_mov_b32_e32 v47, v34
	v_mov_b32_e32 v48, v34
	v_mov_b32_e32 v49, v34
	v_mov_b32_e32 v50, v34
	v_mov_b32_e32 v51, v34
	v_mov_b32_e32 v52, v34
	v_mov_b32_e32 v53, v34
	v_mov_b32_e32 v54, v34
	v_mov_b32_e32 v55, v34
	v_mov_b32_e32 v56, v34
	v_mov_b32_e32 v57, v34
	v_mov_b32_e32 v58, v34
	v_mov_b32_e32 v59, v34
	v_mov_b32_e32 v60, v34
	v_mov_b32_e32 v61, v34
	v_mov_b32_e32 v62, v34
	v_mov_b32_e32 v63, v34
	v_mov_b32_e32 v64, v34
	v_mov_b32_e32 v65, v34
